# prompt attention queue loop: wait for the next unit's prefetched loads at the register hand-over (end of unit) instead of before staging the current unit, so they overlap the unit's compute
# speedup vs baseline: 1.0116x; 1.0026x over previous
.LBB0_986:
	s_or_b64 exec, exec, s[4:5]
	s_add_i32 s4, 0, 0x20184
	v_mov_b32_e32 v0, s4
	s_waitcnt lgkmcnt(0)
	s_barrier
	ds_read_b32 v0, v0
	s_mov_b32 s7, 0
	s_andn2_b64 vcc, exec, s[0:1]
	s_waitcnt lgkmcnt(0)
	v_readfirstlane_b32 s6, v0
	s_cbranch_vccnz .LBB0_1007
	v_add_u32_e32 v0, 0x200, v141
	v_ashrrev_i32_e32 v88, 3, v0
	v_add_u32_e32 v0, 0x400, v141
	v_ashrrev_i32_e32 v89, 3, v0
	v_add_u32_e32 v0, 0x600, v141
	v_ashrrev_i32_e32 v90, 3, v0
	v_lshlrev_b32_e32 v0, 4, v141
	v_and_b32_e32 v0, 0x70, v0
	v_and_b32_e32 v7, 15, v141
	v_readlane_b32 s19, v233, 54
	v_add_u32_e32 v1, 0, v0
	s_movk_i32 s11, 0x90
	v_or_b32_e32 v0, s19, v7
	s_add_i32 s8, s88, 32
	v_mul_lo_u32 v10, v0, s11
	v_or_b32_e32 v0, s8, v7
	s_add_i32 s9, s88, 48
	v_mul_lo_u32 v11, v0, s11
	v_or_b32_e32 v0, s9, v7
	s_add_i32 s12, s88, 64
	v_mul_lo_u32 v12, v0, s11
	v_or_b32_e32 v0, s12, v7
	s_add_i32 s13, s88, 0x50
	v_mul_lo_u32 v13, v0, s11
	v_or_b32_e32 v0, s13, v7
	s_add_i32 s14, s88, 0x60
	v_mul_lo_u32 v14, v0, s11
	v_or_b32_e32 v0, s14, v7
	s_add_i32 s17, s88, 0x70
	v_mul_lo_u32 v15, v0, s11
	v_or_b32_e32 v0, s17, v7
	s_add_i32 s16, s88, 0x80
	v_mul_lo_u32 v16, v0, s11
	v_or_b32_e32 v0, s16, v7
	v_mul_lo_u32 v17, v0, s11
	v_lshrrev_b32_e32 v0, 2, v141
	v_or_b32_e32 v91, s88, v7
	v_and_b32_e32 v0, 12, v0
	v_add_u32_e32 v18, 0x80, v91
	v_or_b32_e32 v19, s88, v0
	v_sub_u32_e32 v20, v18, v19
	s_movk_i32 s10, 0x81
	v_cmp_gt_u32_e64 s[0:1], s10, v20
	v_sub_u32_e32 v20, v19, v18
	s_movk_i32 s15, 0xff7e
	v_writelane_b32 v232, s0, 26
	v_sub_u32_e32 v7, v7, v0
	s_mov_b32 s18, s88
	v_writelane_b32 v232, s1, 27
	v_cmp_lt_u32_e64 s[0:1], s15, v20
	v_mbcnt_lo_u32_b32 v20, -1, 0
	v_mbcnt_hi_u32_b32 v20, -1, v20
	v_writelane_b32 v232, s0, 8
	v_and_b32_e32 v22, 64, v20
	v_xor_b32_e32 v21, 16, v20
	v_writelane_b32 v232, s1, 9
	s_movk_i32 s0, 0x7e
	v_cmp_lt_u32_e64 s[4:5], s0, v19
	v_add_u32_e32 v19, 0x7e, v7
	v_add_u32_e32 v7, 0x7d, v7
	v_writelane_b32 v233, s4, 62
	v_add_u32_e32 v22, 64, v22
	v_cmp_lt_i32_e32 vcc, v21, v22
	v_writelane_b32 v233, s5, 63
	v_cmp_gt_u32_e64 s[4:5], s10, v19
	v_xor_b32_e32 v23, 32, v20
	v_readlane_b32 s1, v233, 53
	v_writelane_b32 v232, s4, 0
	v_cndmask_b32_e32 v21, v20, v21, vcc
	v_cmp_lt_i32_e32 vcc, v23, v22
	v_writelane_b32 v232, s5, 1
	v_cmp_gt_u32_e64 s[4:5], s10, v7
	v_or_b32_e32 v7, s19, v0
	v_sub_u32_e32 v19, v18, v7
	v_writelane_b32 v232, s4, 24
	v_bfe_u32 v22, v141, 2, 4
	s_cmp_gt_u32 s1, 63
	v_writelane_b32 v232, s5, 25
	v_cmp_gt_u32_e64 s[4:5], s10, v19
	v_sub_u32_e32 v19, v7, v18
	v_or_b32_e32 v25, s9, v22
	v_writelane_b32 v232, s4, 16
	v_readlane_b32 s24, v233, 60
	v_or_b32_e32 v24, s19, v22
	v_writelane_b32 v232, s5, 17
	v_cmp_lt_u32_e64 s[4:5], s15, v19
	v_or_b32_e32 v27, s12, v22
	v_readlane_b32 s25, v233, 61
	v_writelane_b32 v232, s4, 18
	v_cndmask_b32_e32 v20, v20, v23, vcc
	v_or_b32_e32 v23, s18, v22
	v_writelane_b32 v232, s5, 19
	v_cmp_lt_u32_e64 s[4:5], s0, v7
	v_sub_u32_e32 v7, v91, v7
	v_add_u32_e32 v19, 0x7e, v7
	v_writelane_b32 v232, s4, 20
	v_add_u32_e32 v7, 0x7d, v7
	v_or_b32_e32 v28, s13, v22
	v_writelane_b32 v232, s5, 21
	v_cmp_gt_u32_e64 s[4:5], s10, v19
	v_lshlrev_b32_e32 v94, 2, v21
	v_mul_lo_u32 v21, v24, s11
	v_writelane_b32 v232, s4, 12
	v_mul_lo_u32 v24, v27, s11
	v_or_b32_e32 v27, s17, v22
	v_writelane_b32 v232, s5, 13
	v_cmp_gt_u32_e64 s[4:5], s10, v7
	v_or_b32_e32 v7, s8, v0
	v_sub_u32_e32 v19, v18, v7
	v_cmp_gt_u32_e64 s[44:45], s10, v19
	v_sub_u32_e32 v19, v7, v18
	v_cmp_lt_u32_e64 s[48:49], s0, v7
	v_sub_u32_e32 v7, v91, v7
	v_cmp_lt_u32_e64 s[46:47], s15, v19
	v_add_u32_e32 v19, 0x7e, v7
	v_add_u32_e32 v7, 0x7d, v7
	v_cmp_gt_u32_e64 s[52:53], s10, v7
	v_or_b32_e32 v7, s9, v0
	v_cmp_gt_u32_e64 s[50:51], s10, v19
	v_sub_u32_e32 v19, v18, v7
	v_cmp_gt_u32_e64 s[54:55], s10, v19
	v_sub_u32_e32 v19, v7, v18
	v_cmp_lt_u32_e64 s[58:59], s0, v7
	v_sub_u32_e32 v7, v91, v7
	v_cmp_lt_u32_e64 s[56:57], s15, v19
	v_add_u32_e32 v19, 0x7e, v7
	v_add_u32_e32 v7, 0x7d, v7
	v_cmp_gt_u32_e64 s[62:63], s10, v7
	v_or_b32_e32 v7, s12, v0
	v_cmp_gt_u32_e64 s[60:61], s10, v19
	v_sub_u32_e32 v19, v18, v7
	v_cmp_gt_u32_e64 s[64:65], s10, v19
	v_sub_u32_e32 v19, v7, v18
	v_cmp_lt_u32_e64 s[68:69], s0, v7
	v_sub_u32_e32 v7, v91, v7
	v_cmp_lt_u32_e64 s[66:67], s15, v19
	v_add_u32_e32 v19, 0x7e, v7
	v_add_u32_e32 v7, 0x7d, v7
	v_cmp_gt_u32_e64 s[72:73], s10, v7
	v_or_b32_e32 v7, s13, v0
	v_cmp_gt_u32_e64 s[70:71], s10, v19
	v_sub_u32_e32 v19, v18, v7
	v_cmp_gt_u32_e64 s[74:75], s10, v19
	v_sub_u32_e32 v19, v7, v18
	v_cmp_lt_u32_e64 s[78:79], s0, v7
	v_sub_u32_e32 v7, v91, v7
	v_cmp_lt_u32_e64 s[76:77], s15, v19
	v_add_u32_e32 v19, 0x7e, v7
	v_add_u32_e32 v7, 0x7d, v7
	v_cmp_gt_u32_e64 s[82:83], s10, v7
	v_or_b32_e32 v7, s14, v0
	v_cmp_gt_u32_e64 s[80:81], s10, v19
	v_sub_u32_e32 v19, v18, v7
	v_cmp_gt_u32_e64 s[84:85], s10, v19
	v_sub_u32_e32 v19, v7, v18
	v_cmp_lt_u32_e64 s[88:89], s0, v7
	v_sub_u32_e32 v7, v91, v7
	v_cmp_lt_u32_e64 s[86:87], s15, v19
	v_add_u32_e32 v19, 0x7e, v7
	v_add_u32_e32 v7, 0x7d, v7
	v_cmp_gt_u32_e64 s[92:93], s10, v7
	v_or_b32_e32 v7, s17, v0
	v_writelane_b32 v232, s4, 14
	v_cmp_gt_u32_e64 s[90:91], s10, v19
	v_sub_u32_e32 v19, v18, v7
	v_writelane_b32 v232, s5, 15
	v_cmp_gt_u32_e64 s[94:95], s10, v19
	v_sub_u32_e32 v19, v7, v18
	v_cmp_lt_u32_e64 s[4:5], s0, v7
	v_sub_u32_e32 v7, v91, v7
	v_cmp_lt_u32_e64 s[96:97], s15, v19
	v_add_u32_e32 v19, 0x7e, v7
	v_add_u32_e32 v7, 0x7d, v7
	v_cmp_gt_u32_e64 s[0:1], s10, v19
	v_or_b32_e32 v19, s8, v22
	v_cmp_gt_u32_e64 s[8:9], s10, v7
	v_or_b32_e32 v7, s16, v0
	s_waitcnt vmcnt(5)
	v_sub_u32_e32 v26, v18, v7
	v_cmp_gt_u32_e64 s[12:13], s10, v26
	v_or_b32_e32 v26, s14, v22
	v_or_b32_e32 v22, s16, v22
	s_load_dwordx4 s[16:19], s[24:25], 0x100
	s_cselect_b64 s[22:23], -1, 0
	v_sub_u32_e32 v18, v7, v18
	v_sub_u32_e32 v7, v91, v7
	v_mul_lo_u32 v92, v91, s11
	s_waitcnt lgkmcnt(0)
	s_add_u32 s16, s18, 0x2b00000
	v_and_b32_e32 v9, 48, v141
	v_cmp_lt_u32_e64 s[14:15], s15, v18
	v_add_u32_e32 v18, 0x7e, v7
	v_add_u32_e32 v29, 0x7d, v7
	v_lshlrev_b32_e32 v95, 2, v20
	v_lshlrev_b32_e32 v7, 3, v140
	v_mul_lo_u32 v20, v23, s11
	v_mul_lo_u32 v19, v19, s11
	v_mul_lo_u32 v23, v25, s11
	v_mul_lo_u32 v25, v28, s11
	v_mul_lo_u32 v26, v26, s11
	v_mul_lo_u32 v27, v27, s11
	v_mul_lo_u32 v22, v22, s11
	s_addc_u32 s17, s19, 0
	v_and_b32_e32 v84, 56, v4
	v_mul_lo_u32 v2, v85, s11
	v_mul_lo_u32 v4, v88, s11
	v_mul_lo_u32 v5, v89, s11
	v_mul_lo_u32 v6, v90, s11
	v_add_u32_e32 v8, 0, v92
	v_add_u32_e32 v93, 0, v9
	v_and_b32_e32 v7, 24, v7
	v_add_u32_e32 v20, 0, v20
	v_add_u32_e32 v21, 0, v21
	v_add_u32_e32 v19, 0, v19
	v_add_u32_e32 v23, 0, v23
	v_add_u32_e32 v24, 0, v24
	v_add_u32_e32 v25, 0, v25
	v_add_u32_e32 v26, 0, v26
	v_add_u32_e32 v27, 0, v27
	v_add_u32_e32 v22, 0, v22
	v_writelane_b32 v233, s16, 54
	v_mov_b32_e32 v3, 0
	v_add_u32_e32 v96, v1, v2
	v_writelane_b32 v233, s17, 55
	v_add_u32_e32 v97, v1, v4
	v_add_u32_e32 v98, v1, v5
	v_add_u32_e32 v99, v1, v6
	v_add_u32_e32 v100, v8, v9
	v_add_u32_e32 v101, v93, v10
	v_add_u32_e32 v102, v93, v11
	v_add_u32_e32 v103, v93, v12
	v_add_u32_e32 v104, v93, v13
	v_add_u32_e32 v105, v93, v14
	v_add_u32_e32 v106, v93, v15
	v_add_u32_e32 v107, v93, v16
	v_add_u32_e32 v108, v93, v17
	v_add_u32_e32 v109, v20, v7
	v_add_u32_e32 v110, v21, v7
	v_add_u32_e32 v111, v19, v7
	v_add_u32_e32 v112, v23, v7
	v_add_u32_e32 v113, v24, v7
	v_add_u32_e32 v114, v25, v7
	v_add_u32_e32 v115, v26, v7
	v_add_u32_e32 v116, v27, v7
	v_add_u32_e32 v117, v22, v7
	s_waitcnt vmcnt(4)
	v_lshlrev_b32_e32 v86, 1, v0
	v_mov_b32_e32 v118, 0xf149f2ca
	v_mov_b32_e32 v119, 0x41b17218
	v_cmp_gt_u32_e64 s[16:17], s10, v18
	v_cmp_gt_u32_e64 s[18:19], s10, v29
	s_movk_i32 s33, 0x3c00
	s_mov_b32 s34, 0
	v_cmp_gt_u32_e64 s[10:11], 16, v140
	s_waitcnt vmcnt(0)
	s_branch .LBB0_989
.LBB0_988:
	s_or_b64 exec, exec, s[26:27]
	s_lshl_b32 s6, s6, 2
	s_add_i32 s6, s6, 0
	s_add_i32 s6, s6, 0x20140
	v_mov_b32_e32 v0, s6
	s_waitcnt lgkmcnt(0)
	s_barrier
	ds_read_b32 v0, v0
	s_waitcnt vmcnt(4)
	v_mov_b64_e32 v[50:51], v[10:11]
	v_mov_b64_e32 v[54:55], v[6:7]
	s_xor_b32 s34, s34, 1
	s_and_b64 vcc, exec, s[24:25]
	s_waitcnt lgkmcnt(0)
	v_readfirstlane_b32 s6, v0
	s_mov_b32 s35, s36
	v_mov_b64_e32 v[48:49], v[8:9]
	v_mov_b64_e32 v[52:53], v[4:5]
	v_mov_b32_e32 v68, v28
	v_mov_b32_e32 v69, v29
	v_mov_b32_e32 v70, v30
	v_mov_b32_e32 v71, v31
	v_mov_b32_e32 v72, v32
	v_mov_b32_e32 v73, v33
	v_mov_b32_e32 v74, v34
	v_mov_b32_e32 v75, v35
	v_mov_b32_e32 v64, v24
	v_mov_b32_e32 v65, v25
	v_mov_b32_e32 v66, v26
	v_mov_b32_e32 v67, v27
	v_mov_b32_e32 v56, v12
	v_mov_b32_e32 v57, v13
	v_mov_b32_e32 v58, v14
	v_mov_b32_e32 v59, v15
	v_mov_b32_e32 v80, v40
	v_mov_b32_e32 v81, v41
	v_mov_b32_e32 v82, v42
	v_mov_b32_e32 v83, v43
	v_mov_b32_e32 v76, v36
	v_mov_b32_e32 v77, v37
	v_mov_b32_e32 v78, v38
	v_mov_b32_e32 v79, v39
	v_mov_b32_e32 v44, v16
	v_mov_b32_e32 v45, v17
	v_mov_b32_e32 v46, v18
	v_mov_b32_e32 v47, v19
	v_mov_b32_e32 v60, v20
	v_mov_b32_e32 v61, v21
	v_mov_b32_e32 v62, v22
	v_mov_b32_e32 v63, v23
	s_cbranch_vccnz .LBB0_1007

.LBB0_1003:
	s_ashr_i32 s6, s35, 8
	s_mul_hi_i32 s26, s6, 0x55555556
	v_add_u32_e32 v0, v93, v92
	s_lshr_b32 s27, s26, 31
	ds_write_b128 v96, v[52:55]
	ds_write_b128 v97, v[48:51]
	ds_write_b128 v96, v[60:63] offset:18432
	ds_write_b128 v96, v[56:59] offset:55296
	ds_write_b128 v97, v[44:47] offset:18432
	ds_write_b128 v97, v[64:67] offset:55296
	ds_write_b128 v98, v[76:79] offset:18432
	ds_write_b128 v98, v[72:75] offset:55296
	ds_write_b128 v99, v[80:83] offset:18432
	ds_write_b128 v99, v[68:71] offset:55296
	s_waitcnt lgkmcnt(0)
	s_barrier
	ds_read_b128 v[52:55], v0 offset:18432
	s_add_i32 s26, s26, s27
	s_mul_i32 s26, s26, 3
	s_sub_i32 s6, s6, s26
	s_lshl_b32 s37, s6, 1
	s_lshr_b32 s26, 64, s37
	ds_read_b128 v[48:51], v100
	ds_read_b128 v[56:59], v0 offset:18496
	s_add_i32 s26, s26, -1
	s_and_b32 s27, s35, 63
	s_and_b32 s38, s26, s27
	s_sub_i32 s26, 6, s37
	s_lshr_b32 s27, s27, s26
	s_ashr_i32 s26, s35, 6
	ds_read_b128 v[44:47], v100 offset:64
	s_and_b32 s35, s26, 3
	s_mul_hi_i32 s26, s26, 0x2aaaaaab
	s_waitcnt lgkmcnt(2)
	v_mfma_f32_16x16x32_bf16 v[52:55], v[52:55], v[48:51], 0
	s_lshr_b32 s28, s26, 31
	s_ashr_i32 s26, s26, 1
	s_add_i32 s28, s26, s28
	s_ashr_i32 s29, s28, 31
	s_lshl_b32 s26, s35, 6
	s_lshl_b32 s30, s6, 8
	s_or_b32 s26, s30, s26
	s_lshl_b64 s[28:29], s[28:29], 13
	s_waitcnt lgkmcnt(0)
	v_mfma_f32_16x16x32_bf16 v[52:55], v[56:59], v[44:47], v[52:55]
	s_cmp_lg_u32 s38, 0
	v_readlane_b32 s40, v233, 51
	s_cselect_b64 s[30:31], -1, 0
	v_readlane_b32 s41, v233, 52
	v_readlane_b32 vcc_lo, v232, 26
	s_or_b64 s[40:41], s[40:41], s[30:31]
	v_readlane_b32 vcc_hi, v232, 27
	v_readlane_b32 s42, v233, 62
	v_mul_f32_e32 v0, 0x3e000000, v52
	s_and_b64 vcc, vcc, s[40:41]
	v_readlane_b32 s43, v233, 63
	ds_read_b128 v[56:59], v101 offset:18432
	ds_read_b128 v[60:63], v101 offset:18496
	v_cndmask_b32_e32 v0, v118, v0, vcc
	s_or_b64 vcc, s[42:43], s[30:31]
	v_readlane_b32 s42, v232, 8
	v_readlane_b32 s43, v232, 9
	s_and_b64 vcc, s[42:43], vcc
	v_readlane_b32 s42, v232, 0
	v_mul_f32_e32 v1, 0x3e000000, v53
	v_readlane_b32 s43, v232, 1
	s_waitcnt lgkmcnt(1)
	v_mfma_f32_16x16x32_bf16 v[56:59], v[56:59], v[48:51], 0
	v_cndmask_b32_e32 v1, v118, v1, vcc
	s_and_b64 vcc, s[42:43], s[40:41]
	v_readlane_b32 s42, v232, 24
	v_mul_f32_e32 v2, 0x3e000000, v54
	v_readlane_b32 s43, v232, 25
	v_cndmask_b32_e32 v2, v118, v2, vcc
	v_mul_f32_e32 v52, 0x3e000000, v55
	s_and_b64 vcc, s[42:43], s[40:41]
	v_cndmask_b32_e32 v64, v118, v52, vcc
	s_waitcnt lgkmcnt(0)
	v_mfma_f32_16x16x32_bf16 v[52:55], v[60:63], v[44:47], v[56:59]
	v_readlane_b32 s40, v233, 49
	v_readlane_b32 s41, v233, 50
	v_readlane_b32 s42, v232, 16
	s_or_b64 s[40:41], s[40:41], s[30:31]
	v_readlane_b32 s43, v232, 17
	s_and_b64 vcc, s[42:43], s[40:41]
	v_readlane_b32 s42, v232, 20
	s_nop 0
	v_mul_f32_e32 v52, 0x3e000000, v52
	v_readlane_b32 s43, v232, 21
	ds_read_b128 v[56:59], v102 offset:18432
	ds_read_b128 v[60:63], v102 offset:18496
	v_cndmask_b32_e32 v65, v118, v52, vcc
	s_or_b64 vcc, s[42:43], s[30:31]
	v_readlane_b32 s42, v232, 18
	v_readlane_b32 s43, v232, 19
	s_and_b64 vcc, s[42:43], vcc
	v_readlane_b32 s42, v232, 12
	v_mul_f32_e32 v52, 0x3e000000, v53
	v_readlane_b32 s43, v232, 13
	s_waitcnt lgkmcnt(1)
	v_mfma_f32_16x16x32_bf16 v[56:59], v[56:59], v[48:51], 0
	v_cndmask_b32_e32 v66, v118, v52, vcc
	s_and_b64 vcc, s[42:43], s[40:41]
	v_readlane_b32 s42, v232, 14
	v_mul_f32_e32 v52, 0x3e000000, v54
	v_readlane_b32 s43, v232, 15
	v_cndmask_b32_e32 v67, v118, v52, vcc
	v_mul_f32_e32 v52, 0x3e000000, v55
	s_and_b64 vcc, s[42:43], s[40:41]
	v_cndmask_b32_e32 v68, v118, v52, vcc
	s_waitcnt lgkmcnt(0)
	v_mfma_f32_16x16x32_bf16 v[52:55], v[60:63], v[44:47], v[56:59]
	v_readlane_b32 s40, v233, 47
	s_nop 1
	ds_read_b128 v[56:59], v103 offset:18432
	ds_read_b128 v[60:63], v103 offset:18496
	v_readlane_b32 s41, v233, 48
	s_or_b64 s[40:41], s[40:41], s[30:31]
	s_nop 0
	v_mul_f32_e32 v52, 0x3e000000, v52
	s_and_b64 vcc, s[44:45], s[40:41]
	v_cndmask_b32_e32 v69, v118, v52, vcc
	s_or_b64 vcc, s[48:49], s[30:31]
	s_waitcnt lgkmcnt(1)
	v_mfma_f32_16x16x32_bf16 v[56:59], v[56:59], v[48:51], 0
	v_mul_f32_e32 v52, 0x3e000000, v53
	s_and_b64 vcc, s[46:47], vcc
	v_cndmask_b32_e32 v70, v118, v52, vcc
	v_mul_f32_e32 v52, 0x3e000000, v54
	s_and_b64 vcc, s[50:51], s[40:41]
	v_cndmask_b32_e32 v71, v118, v52, vcc
	v_mul_f32_e32 v52, 0x3e000000, v55
	s_and_b64 vcc, s[52:53], s[40:41]
	v_cndmask_b32_e32 v72, v118, v52, vcc
	s_waitcnt lgkmcnt(0)
	v_mfma_f32_16x16x32_bf16 v[52:55], v[60:63], v[44:47], v[56:59]
	v_readlane_b32 s40, v233, 45
	s_nop 1
	ds_read_b128 v[56:59], v104 offset:18432
	ds_read_b128 v[60:63], v104 offset:18496
	v_readlane_b32 s41, v233, 46
	s_or_b64 s[40:41], s[40:41], s[30:31]
	s_nop 0
	v_mul_f32_e32 v52, 0x3e000000, v52
	s_and_b64 vcc, s[54:55], s[40:41]
	v_cndmask_b32_e32 v73, v118, v52, vcc
	s_or_b64 vcc, s[58:59], s[30:31]
	s_waitcnt lgkmcnt(1)
	v_mfma_f32_16x16x32_bf16 v[56:59], v[56:59], v[48:51], 0
	v_mul_f32_e32 v52, 0x3e000000, v53
	s_and_b64 vcc, s[56:57], vcc
	v_cndmask_b32_e32 v74, v118, v52, vcc
	v_mul_f32_e32 v52, 0x3e000000, v54
	s_and_b64 vcc, s[60:61], s[40:41]
	v_cndmask_b32_e32 v75, v118, v52, vcc
	v_mul_f32_e32 v52, 0x3e000000, v55
	s_and_b64 vcc, s[62:63], s[40:41]
	v_cndmask_b32_e32 v76, v118, v52, vcc
	s_waitcnt lgkmcnt(0)
	v_mfma_f32_16x16x32_bf16 v[52:55], v[60:63], v[44:47], v[56:59]
	v_readlane_b32 s40, v233, 43
	s_nop 1
	ds_read_b128 v[56:59], v105 offset:18432
	ds_read_b128 v[60:63], v105 offset:18496
	v_readlane_b32 s41, v233, 44
	s_or_b64 s[40:41], s[40:41], s[30:31]
	s_nop 0
	v_mul_f32_e32 v52, 0x3e000000, v52
	s_and_b64 vcc, s[64:65], s[40:41]
	v_cndmask_b32_e32 v77, v118, v52, vcc
	s_or_b64 vcc, s[68:69], s[30:31]
	s_waitcnt lgkmcnt(1)
	v_mfma_f32_16x16x32_bf16 v[56:59], v[56:59], v[48:51], 0
	v_mul_f32_e32 v52, 0x3e000000, v53
	s_and_b64 vcc, s[66:67], vcc
	v_cndmask_b32_e32 v78, v118, v52, vcc
	v_mul_f32_e32 v52, 0x3e000000, v54
	s_and_b64 vcc, s[70:71], s[40:41]
	v_cndmask_b32_e32 v79, v118, v52, vcc
	v_mul_f32_e32 v52, 0x3e000000, v55
	s_and_b64 vcc, s[72:73], s[40:41]
	v_cndmask_b32_e32 v80, v118, v52, vcc
	s_waitcnt lgkmcnt(0)
	v_mfma_f32_16x16x32_bf16 v[52:55], v[60:63], v[44:47], v[56:59]
	v_readlane_b32 s40, v233, 41
	s_nop 1
	ds_read_b128 v[56:59], v106 offset:18432
	ds_read_b128 v[60:63], v106 offset:18496
	v_readlane_b32 s41, v233, 42
	s_or_b64 s[40:41], s[40:41], s[30:31]
	s_nop 0
	v_mul_f32_e32 v52, 0x3e000000, v52
	s_and_b64 vcc, s[74:75], s[40:41]
	v_cndmask_b32_e32 v81, v118, v52, vcc
	s_or_b64 vcc, s[78:79], s[30:31]
	s_waitcnt lgkmcnt(1)
	v_mfma_f32_16x16x32_bf16 v[56:59], v[56:59], v[48:51], 0
	v_mul_f32_e32 v52, 0x3e000000, v53
	s_and_b64 vcc, s[76:77], vcc
	v_cndmask_b32_e32 v82, v118, v52, vcc
	v_mul_f32_e32 v52, 0x3e000000, v54
	s_and_b64 vcc, s[80:81], s[40:41]
	v_cndmask_b32_e32 v83, v118, v52, vcc
	v_mul_f32_e32 v52, 0x3e000000, v55
	s_and_b64 vcc, s[82:83], s[40:41]
	v_cndmask_b32_e32 v87, v118, v52, vcc
	s_waitcnt lgkmcnt(0)
	v_mfma_f32_16x16x32_bf16 v[52:55], v[60:63], v[44:47], v[56:59]
	v_readlane_b32 s40, v233, 39
	s_nop 1
	ds_read_b128 v[56:59], v107 offset:18432
	ds_read_b128 v[60:63], v107 offset:18496
	v_readlane_b32 s41, v233, 40
	s_or_b64 s[40:41], s[40:41], s[30:31]
	s_nop 0
	v_mul_f32_e32 v52, 0x3e000000, v52
	s_and_b64 vcc, s[84:85], s[40:41]
	v_cndmask_b32_e32 v121, v118, v52, vcc
	s_or_b64 vcc, s[88:89], s[30:31]
	s_waitcnt lgkmcnt(1)
	v_mfma_f32_16x16x32_bf16 v[56:59], v[56:59], v[48:51], 0
	v_mul_f32_e32 v52, 0x3e000000, v53
	s_and_b64 vcc, s[86:87], vcc
	v_cndmask_b32_e32 v122, v118, v52, vcc
	v_mul_f32_e32 v52, 0x3e000000, v54
	s_and_b64 vcc, s[90:91], s[40:41]
	v_cndmask_b32_e32 v123, v118, v52, vcc
	v_mul_f32_e32 v52, 0x3e000000, v55
	s_and_b64 vcc, s[92:93], s[40:41]
	v_cndmask_b32_e32 v124, v118, v52, vcc
	s_waitcnt lgkmcnt(0)
	v_mfma_f32_16x16x32_bf16 v[52:55], v[60:63], v[44:47], v[56:59]
	s_nop 2
	ds_read_b128 v[56:59], v108 offset:18432
	ds_read_b128 v[60:63], v108 offset:18496
	s_or_b64 s[40:41], s[22:23], s[30:31]
	s_and_b64 vcc, s[94:95], s[40:41]
	s_waitcnt lgkmcnt(1)
	v_mfma_f32_16x16x32_bf16 v[48:51], v[56:59], v[48:51], 0
	v_mul_f32_e32 v52, 0x3e000000, v52
	s_or_b64 s[30:31], s[4:5], s[30:31]
	v_cndmask_b32_e32 v52, v118, v52, vcc
	s_and_b64 vcc, s[96:97], s[30:31]
	s_mov_b32 s30, 0xf149f2ca
	v_max3_f32 v56, v0, s30, v1
	s_waitcnt lgkmcnt(0)
	v_mfma_f32_16x16x32_bf16 v[44:47], v[60:63], v[44:47], v[48:51]
	v_mul_f32_e32 v53, 0x3e000000, v53
	v_cndmask_b32_e32 v53, v118, v53, vcc
	v_mul_f32_e32 v54, 0x3e000000, v54
	v_max3_f32 v48, v56, v2, v64
	v_max3_f32 v48, v48, v65, v66
	v_max3_f32 v48, v48, v67, v68
	v_max3_f32 v48, v48, v69, v70
	v_max3_f32 v48, v48, v71, v72
	v_max3_f32 v48, v48, v73, v74
	v_max3_f32 v48, v48, v75, v76
	v_max3_f32 v48, v48, v77, v78
	v_max3_f32 v48, v48, v79, v80
	v_max3_f32 v48, v48, v81, v82
	v_max3_f32 v48, v48, v83, v87
	s_and_b64 vcc, s[0:1], s[40:41]
	v_max3_f32 v48, v48, v121, v122
	v_cndmask_b32_e32 v54, v118, v54, vcc
	v_mul_f32_e32 v55, 0x3e000000, v55
	s_and_b64 vcc, s[8:9], s[40:41]
	v_max3_f32 v48, v48, v123, v124
	v_mul_f32_e32 v44, 0x3e000000, v44
	v_cndmask_b32_e32 v55, v118, v55, vcc
	v_max3_f32 v48, v48, v52, v53
	v_cndmask_b32_e64 v49, v118, v44, s[12:13]
	v_mul_f32_e32 v44, 0x3e000000, v45
	v_mul_f32_e32 v46, 0x3e000000, v46
	v_max3_f32 v48, v48, v54, v55
	v_cndmask_b32_e64 v45, v118, v44, s[14:15]
	v_cndmask_b32_e64 v125, v118, v46, s[16:17]
	v_mul_f32_e32 v46, 0x3e000000, v47
	v_max3_f32 v44, v48, v49, v45
	v_cndmask_b32_e64 v126, v118, v46, s[18:19]
	v_max3_f32 v44, v44, v125, v126
	ds_bpermute_b32 v46, v94, v44
	s_waitcnt lgkmcnt(0)
	v_max_f32_e32 v46, v46, v46
	v_max_f32_e32 v44, v44, v46
	ds_bpermute_b32 v46, v95, v44
	s_waitcnt lgkmcnt(0)
	v_max_f32_e32 v46, v46, v46
	v_max_f32_e32 v44, v44, v46
	v_sub_f32_e32 v47, v64, v44
	v_mul_f32_e32 v47, 0x3fb8aa3b, v47
	v_exp_f32_e32 v48, v47
	v_sub_f32_e32 v47, v65, v44
	v_mul_f32_e32 v47, 0x3fb8aa3b, v47
	v_exp_f32_e32 v58, v47
	v_sub_f32_e32 v47, v66, v44
	v_mul_f32_e32 v47, 0x3fb8aa3b, v47
	v_exp_f32_e32 v59, v47
	v_sub_f32_e32 v47, v67, v44
	v_mul_f32_e32 v47, 0x3fb8aa3b, v47
	v_exp_f32_e32 v60, v47
	v_sub_f32_e32 v47, v68, v44
	v_mul_f32_e32 v47, 0x3fb8aa3b, v47
	v_exp_f32_e32 v61, v47
	v_sub_f32_e32 v47, v69, v44
	v_mul_f32_e32 v47, 0x3fb8aa3b, v47
	v_exp_f32_e32 v127, v47
	v_sub_f32_e32 v47, v70, v44
	v_mul_f32_e32 v47, 0x3fb8aa3b, v47
	v_exp_f32_e32 v70, v47
	v_sub_f32_e32 v47, v71, v44
	v_mul_f32_e32 v47, 0x3fb8aa3b, v47
	v_exp_f32_e32 v71, v47
	v_sub_f32_e32 v47, v72, v44
	v_mul_f32_e32 v47, 0x3fb8aa3b, v47
	v_exp_f32_e32 v72, v47
	v_sub_f32_e32 v47, v73, v44
	v_mul_f32_e32 v47, 0x3fb8aa3b, v47
	v_exp_f32_e32 v73, v47
	v_sub_f32_e32 v47, v74, v44
	v_mul_f32_e32 v47, 0x3fb8aa3b, v47
	v_exp_f32_e32 v74, v47
	v_sub_f32_e32 v47, v75, v44
	v_mul_f32_e32 v47, 0x3fb8aa3b, v47
	v_exp_f32_e32 v75, v47
	v_sub_f32_e32 v47, v76, v44
	v_mul_f32_e32 v47, 0x3fb8aa3b, v47
	v_sub_f32_e32 v0, v0, v44
	v_exp_f32_e32 v76, v47
	v_sub_f32_e32 v47, v77, v44
	v_mul_f32_e32 v0, 0x3fb8aa3b, v0
	v_sub_f32_e32 v1, v1, v44
	v_mul_f32_e32 v47, 0x3fb8aa3b, v47
	v_exp_f32_e32 v0, v0
	v_mul_f32_e32 v1, 0x3fb8aa3b, v1
	v_sub_f32_e32 v2, v2, v44
	v_exp_f32_e32 v128, v47
	v_sub_f32_e32 v47, v78, v44
	v_exp_f32_e32 v1, v1
	v_mul_f32_e32 v2, 0x3fb8aa3b, v2
	v_mul_f32_e32 v47, 0x3fb8aa3b, v47
	v_exp_f32_e32 v2, v2
	v_exp_f32_e32 v129, v47
	v_sub_f32_e32 v47, v79, v44
	v_mul_f32_e32 v47, 0x3fb8aa3b, v47
	v_add_f32_e32 v46, 0, v0
	v_exp_f32_e32 v130, v47
	v_sub_f32_e32 v47, v80, v44
	v_add_f32_e32 v46, v1, v46
	v_mul_f32_e32 v47, 0x3fb8aa3b, v47
	v_add_f32_e32 v46, v2, v46
	v_exp_f32_e32 v131, v47
	v_sub_f32_e32 v47, v81, v44
	v_add_f32_e32 v46, v48, v46
	v_mul_f32_e32 v47, 0x3fb8aa3b, v47
	v_add_f32_e32 v46, v58, v46
	v_exp_f32_e32 v132, v47
	v_sub_f32_e32 v47, v82, v44
	v_add_f32_e32 v46, v59, v46
	v_mul_f32_e32 v47, 0x3fb8aa3b, v47
	v_add_f32_e32 v46, v60, v46
	v_exp_f32_e32 v82, v47
	v_sub_f32_e32 v47, v83, v44
	v_add_f32_e32 v46, v61, v46
	v_mul_f32_e32 v47, 0x3fb8aa3b, v47
	v_add_f32_e32 v46, v127, v46
	v_exp_f32_e32 v83, v47
	v_sub_f32_e32 v47, v87, v44
	v_add_f32_e32 v46, v70, v46
	v_mul_f32_e32 v47, 0x3fb8aa3b, v47
	v_add_f32_e32 v46, v71, v46
	v_exp_f32_e32 v87, v47
	v_sub_f32_e32 v47, v121, v44
	v_add_f32_e32 v46, v72, v46
	v_mul_f32_e32 v47, 0x3fb8aa3b, v47
	v_add_f32_e32 v46, v73, v46
	v_exp_f32_e32 v121, v47
	v_sub_f32_e32 v47, v122, v44
	v_add_f32_e32 v46, v74, v46
	v_mul_f32_e32 v47, 0x3fb8aa3b, v47
	v_add_f32_e32 v46, v75, v46
	v_exp_f32_e32 v122, v47
	v_sub_f32_e32 v47, v123, v44
	v_add_f32_e32 v46, v76, v46
	v_mul_f32_e32 v47, 0x3fb8aa3b, v47
	v_add_f32_e32 v46, v128, v46
	v_exp_f32_e32 v123, v47
	v_sub_f32_e32 v47, v124, v44
	v_add_f32_e32 v46, v129, v46
	v_mul_f32_e32 v47, 0x3fb8aa3b, v47
	v_add_f32_e32 v46, v130, v46
	v_exp_f32_e32 v124, v47
	v_sub_f32_e32 v47, v52, v44
	v_add_f32_e32 v46, v131, v46
	v_mul_f32_e32 v47, 0x3fb8aa3b, v47
	v_add_f32_e32 v46, v132, v46
	v_exp_f32_e32 v133, v47
	v_sub_f32_e32 v47, v53, v44
	v_add_f32_e32 v46, v82, v46
	v_mul_f32_e32 v47, 0x3fb8aa3b, v47
	v_add_f32_e32 v46, v83, v46
	v_exp_f32_e32 v134, v47
	v_sub_f32_e32 v47, v54, v44
	v_add_f32_e32 v46, v87, v46
	v_mul_f32_e32 v47, 0x3fb8aa3b, v47
	v_add_f32_e32 v46, v121, v46
	v_exp_f32_e32 v135, v47
	v_sub_f32_e32 v47, v55, v44
	v_add_f32_e32 v46, v122, v46
	v_mul_f32_e32 v47, 0x3fb8aa3b, v47
	v_add_f32_e32 v46, v123, v46
	v_exp_f32_e32 v136, v47
	v_sub_f32_e32 v47, v49, v44
	v_add_f32_e32 v46, v124, v46
	v_mul_f32_e32 v47, 0x3fb8aa3b, v47
	v_sub_f32_e32 v45, v45, v44
	v_cvt_pk_bf16_f32 v50, v0, v1
	v_sub_f32_e32 v0, v125, v44
	v_add_f32_e32 v46, v133, v46
	v_exp_f32_e32 v137, v47
	v_mul_f32_e32 v45, 0x3fb8aa3b, v45
	v_mul_f32_e32 v0, 0x3fb8aa3b, v0
	v_add_f32_e32 v46, v134, v46
	v_exp_f32_e32 v138, v45
	v_exp_f32_e32 v1, v0
	v_sub_f32_e32 v0, v126, v44
	v_add_f32_e32 v46, v135, v46
	v_mul_f32_e32 v0, 0x3fb8aa3b, v0
	v_add_f32_e32 v66, v136, v46
	ds_read_b64_tr_b16 v[46:47], v109 offset:55296
	v_cvt_pk_bf16_f32 v51, v2, v48
	v_exp_f32_e32 v2, v0
	v_add_f32_e32 v0, v137, v66
	v_add_f32_e32 v0, v138, v0
	v_add_f32_e32 v0, v1, v0
	v_add_f32_e32 v0, v2, v0
	ds_read_b64_tr_b16 v[48:49], v110 offset:55296
	ds_read_b64_tr_b16 v[56:57], v110 offset:55328
	ds_bpermute_b32 v45, v94, v0
	v_cvt_pk_bf16_f32 v52, v58, v59
	v_cvt_pk_bf16_f32 v53, v60, v61
	ds_read_b64_tr_b16 v[54:55], v109 offset:55328
	ds_read_b64_tr_b16 v[58:59], v109 offset:55360
	ds_read_b64_tr_b16 v[62:63], v109 offset:55392
	ds_read_b64_tr_b16 v[60:61], v110 offset:55360
	ds_read_b64_tr_b16 v[64:65], v110 offset:55392
	ds_read_b64_tr_b16 v[68:69], v112 offset:55296
	ds_read_b64_tr_b16 v[66:67], v111 offset:55296
	s_waitcnt lgkmcnt(9)
	v_mfma_f32_16x16x32_bf16 v[46:49], v[46:49], v[50:53], 0
	s_waitcnt lgkmcnt(7)
	v_add_f32_e32 v0, v0, v45
	ds_bpermute_b32 v45, v95, v0
	v_cvt_pk_bf16_f32 v1, v1, v2
	s_waitcnt lgkmcnt(7)
	v_mfma_f32_16x16x32_bf16 v[54:57], v[54:57], v[50:53], 0
	v_mov_b32_e32 v2, v3
	s_waitcnt lgkmcnt(0)
	v_add_f32_e32 v45, v0, v45
	v_mfma_f32_16x16x32_bf16 v[58:61], v[58:61], v[50:53], 0
	v_div_scale_f32 v0, s[30:31], v45, v45, 1.0
	v_mfma_f32_16x16x32_bf16 v[50:53], v[62:65], v[50:53], 0
	v_cvt_pk_bf16_f32 v62, v127, v70
	v_cvt_pk_bf16_f32 v63, v71, v72
	v_cvt_pk_bf16_f32 v64, v73, v74
	v_cvt_pk_bf16_f32 v65, v75, v76
	ds_read_b64_tr_b16 v[72:73], v112 offset:55328
	ds_read_b64_tr_b16 v[70:71], v111 offset:55328
	ds_read_b64_tr_b16 v[74:75], v111 offset:55360
	ds_read_b64_tr_b16 v[78:79], v111 offset:55392
	ds_read_b64_tr_b16 v[76:77], v112 offset:55360
	ds_read_b64_tr_b16 v[80:81], v112 offset:55392
	v_mfma_f32_16x16x32_bf16 v[46:49], v[66:69], v[62:65], v[46:49]
	ds_read_b64_tr_b16 v[66:67], v113 offset:55296
	s_waitcnt lgkmcnt(5)
	v_mfma_f32_16x16x32_bf16 v[54:57], v[70:73], v[62:65], v[54:57]
	ds_read_b64_tr_b16 v[68:69], v114 offset:55296
	ds_read_b64_tr_b16 v[72:73], v114 offset:55328
	s_waitcnt lgkmcnt(4)
	v_mfma_f32_16x16x32_bf16 v[58:61], v[74:77], v[62:65], v[58:61]
	s_waitcnt lgkmcnt(3)
	v_mfma_f32_16x16x32_bf16 v[50:53], v[78:81], v[62:65], v[50:53]
	v_cvt_pk_bf16_f32 v64, v132, v82
	v_rcp_f32_e32 v82, v0
	v_cvt_pk_bf16_f32 v62, v128, v129
	v_cvt_pk_bf16_f32 v63, v130, v131
	v_cvt_pk_bf16_f32 v65, v83, v87
	ds_read_b64_tr_b16 v[70:71], v113 offset:55328
	ds_read_b64_tr_b16 v[74:75], v113 offset:55360
	ds_read_b64_tr_b16 v[78:79], v113 offset:55392
	ds_read_b64_tr_b16 v[76:77], v114 offset:55360
	ds_read_b64_tr_b16 v[80:81], v114 offset:55392
	s_waitcnt lgkmcnt(6)
	v_mfma_f32_16x16x32_bf16 v[46:49], v[66:69], v[62:65], v[46:49]
	v_fma_f32 v66, -v0, v82, 1.0
	v_fmac_f32_e32 v82, v66, v82
	ds_read_b64_tr_b16 v[68:69], v116 offset:55296
	ds_read_b64_tr_b16 v[66:67], v115 offset:55296
	s_waitcnt lgkmcnt(6)
	v_mfma_f32_16x16x32_bf16 v[54:57], v[70:73], v[62:65], v[54:57]
	v_mov_b32_e32 v87, v3
	s_waitcnt lgkmcnt(3)
	v_mfma_f32_16x16x32_bf16 v[58:61], v[74:77], v[62:65], v[58:61]
	s_waitcnt lgkmcnt(2)
	v_mfma_f32_16x16x32_bf16 v[50:53], v[78:81], v[62:65], v[50:53]
	v_cvt_pk_bf16_f32 v62, v121, v122
	v_cvt_pk_bf16_f32 v63, v123, v124
	v_cvt_pk_bf16_f32 v64, v133, v134
	v_cvt_pk_bf16_f32 v65, v135, v136
	ds_read_b64_tr_b16 v[70:71], v115 offset:55328
	ds_read_b64_tr_b16 v[74:75], v115 offset:55360
	ds_read_b64_tr_b16 v[78:79], v115 offset:55392
	ds_read_b64_tr_b16 v[72:73], v116 offset:55328
	ds_read_b64_tr_b16 v[76:77], v116 offset:55360
	ds_read_b64_tr_b16 v[80:81], v116 offset:55392
	s_waitcnt lgkmcnt(6)
	v_mfma_f32_16x16x32_bf16 v[46:49], v[66:69], v[62:65], v[46:49]
	v_div_scale_f32 v66, vcc, 1.0, v45, 1.0
	v_mul_f32_e32 v67, v66, v82
	v_fma_f32 v68, -v0, v67, v66
	v_fmac_f32_e32 v67, v68, v82
	v_fma_f32 v0, -v0, v67, v66
	v_div_fmas_f32 v82, v0, v82, v67
	ds_read_b64_tr_b16 v[66:67], v117 offset:55296
	s_waitcnt lgkmcnt(3)
	v_mfma_f32_16x16x32_bf16 v[54:57], v[70:73], v[62:65], v[54:57]
	v_mov_b32_e32 v68, v3
	v_mov_b32_e32 v69, v3
	v_mov_b32_e32 v72, v3
	s_waitcnt lgkmcnt(2)
	v_mfma_f32_16x16x32_bf16 v[58:61], v[74:77], v[62:65], v[58:61]
	v_mov_b32_e32 v73, v3
	v_mov_b32_e32 v76, v3
	v_mov_b32_e32 v77, v3
	s_waitcnt lgkmcnt(1)
	v_mfma_f32_16x16x32_bf16 v[50:53], v[78:81], v[62:65], v[50:53]
	ds_read_b64_tr_b16 v[62:63], v117 offset:55328
	ds_read_b64_tr_b16 v[70:71], v117 offset:55360
	ds_read_b64_tr_b16 v[74:75], v117 offset:55392
	v_mov_b32_e32 v64, v3
	v_mov_b32_e32 v65, v3
	v_lshl_add_u32 v0, s38, 7, v91
	v_lshlrev_b32_e32 v83, s37, v0
	v_cvt_pk_bf16_f32 v0, v137, v138
	s_waitcnt lgkmcnt(3)
	s_nop 0
	v_mfma_f32_16x16x32_bf16 v[46:49], v[66:69], v[0:3], v[46:49]
	s_waitcnt lgkmcnt(2)
	v_mfma_f32_16x16x32_bf16 v[54:57], v[62:65], v[0:3], v[54:57]
	s_waitcnt lgkmcnt(1)
	v_mfma_f32_16x16x32_bf16 v[58:61], v[70:73], v[0:3], v[58:61]
	s_waitcnt lgkmcnt(0)
	v_mfma_f32_16x16x32_bf16 v[50:53], v[74:77], v[0:3], v[50:53]
	v_add_u32_e32 v2, s27, v83
	v_lshl_add_u64 v[0:1], s[28:29], 0, v[2:3]
	v_readlane_b32 s28, v233, 9
	v_readlane_b32 s29, v233, 10
	s_movk_i32 s27, 0x600
	v_div_fixup_f32 v2, v82, v45, 1.0
	v_mov_b64_e32 v[62:63], s[28:29]
	v_mad_u64_u32 v[62:63], s[28:29], v0, s27, v[62:63]
	v_mad_i32_i24 v63, v1, s27, v63
	s_ashr_i32 s27, s26, 31
	v_lshl_add_u64 v[62:63], s[26:27], 1, v[62:63]
	v_pk_mul_f32 v[48:49], v[2:3], v[48:49] op_sel_hi:[0,1]
	v_pk_mul_f32 v[46:47], v[2:3], v[46:47] op_sel_hi:[0,1]
	v_lshl_add_u64 v[62:63], v[62:63], 0, v[86:87]
	v_cvt_pk_bf16_f32 v46, v46, v47
	v_cvt_pk_bf16_f32 v47, v48, v49
	global_store_dwordx2 v[62:63], v[46:47], off
	v_pk_mul_f32 v[46:47], v[2:3], v[56:57] op_sel_hi:[0,1]
	v_pk_mul_f32 v[48:49], v[2:3], v[54:55] op_sel_hi:[0,1]
	v_cvt_pk_bf16_f32 v48, v48, v49
	v_cvt_pk_bf16_f32 v49, v46, v47
	global_store_dwordx2 v[62:63], v[48:49], off offset:32
	v_pk_mul_f32 v[46:47], v[2:3], v[60:61] op_sel_hi:[0,1]
	v_pk_mul_f32 v[48:49], v[2:3], v[58:59] op_sel_hi:[0,1]
	v_cvt_pk_bf16_f32 v48, v48, v49
	v_cvt_pk_bf16_f32 v49, v46, v47
	global_store_dwordx2 v[62:63], v[48:49], off offset:64
	v_pk_mul_f32 v[46:47], v[2:3], v[52:53] op_sel_hi:[0,1]
	v_pk_mul_f32 v[48:49], v[2:3], v[50:51] op_sel_hi:[0,1]
	v_cvt_pk_bf16_f32 v48, v48, v49
	v_cvt_pk_bf16_f32 v49, v46, v47
	global_store_dwordx2 v[62:63], v[48:49], off offset:96
	s_and_saveexec_b64 s[26:27], s[10:11]
	s_cbranch_execz .LBB0_1005
	s_mov_b32 s28, 0x800000
	v_cmp_gt_f32_e32 vcc, s28, v45
	s_mov_b32 s28, 0x3f317217
	v_readlane_b32 s30, v233, 54
	v_cndmask_b32_e64 v2, 0, 32, vcc
	v_ldexp_f32 v2, v45, v2
	v_log_f32_e32 v2, v2
	v_cndmask_b32_e32 v45, 0, v119, vcc
	v_readlane_b32 s31, v233, 55
	v_mul_f32_e32 v46, 0x3f317217, v2
	v_fma_f32 v46, v2, s28, -v46
	v_fmac_f32_e32 v46, 0x3377d1cf, v2
	s_mov_b32 s28, 0x7f800000
	v_fmac_f32_e32 v46, 0x3f317217, v2
	v_cmp_lt_f32_e64 vcc, |v2|, s28
	s_lshl_b32 s28, s6, 2
	s_ashr_i32 s29, s28, 31
	v_cndmask_b32_e32 v2, v2, v46, vcc
	v_sub_f32_e32 v2, v2, v45
	v_add_f32_e32 v2, v44, v2
	v_mad_u64_u32 v[44:45], s[30:31], v0, 48, s[30:31]
	v_mad_i32_i24 v45, v1, 48, v45
	v_lshl_add_u64 v[0:1], s[28:29], 2, v[44:45]
	s_lshl_b32 s6, s35, 2
	v_lshl_add_u64 v[0:1], v[0:1], 0, s[6:7]
	global_store_dword v[0:1], v2, off
